# merge epilogue: the running-sum load the compiler sank behind a vmcnt(0) before its use is issued with its batch into dead fragment VGPRs v[232:235]; bit-identical
# speedup vs baseline: 1.0058x; 1.0058x over previous
; DEV float bf2f(u16 h) { return __uint_as_float(((unsigned)h) << 16); }
; DEV float sigm_f(float v) { return 1.f / (1.f + __expf(-v)); }
; DEV void phase_gemm(const Params& p, int l, int mode) {
;     ...
;         const u16* MG = (const u16*)(ws + OFF_MG);
;         u16* MH = (u16*)(ws + OFF_KROW); u16* MB = (u16*)(ws + OFF_VT);
;         const bool ex = cur.extra != 0;
;         const bool rd = !ex && sb > 0;
;     ...
; #pragma unroll
;         for (int hb = 0; hb < 4; ++hb) {
;           bf16x8 g[4], pm_[4];
; #pragma unroll
;           for (int qq = 0; qq < 4; ++qq) { M1_ADDR(hb * 4 + qq); g[qq] = __builtin_nontemporal_load(reinterpret_cast<const bf16x8*>(MG + R_ * 3072 + sb * 1024 + cc_)); pm_[qq] = *reinterpret_cast<const bf16x8*>(MH + R_ * 1024 + cc_); }
; #pragma unroll
;           for (int qq = 0; qq < 4; ++qq) {
;             M1_ADDR(hb * 4 + qq);
;             f32x4 v0 = acc[ai_][bj_][m_][0], v1 = acc[ai_][bj_][m_][1];
; #pragma unroll
;             for (int e = 0; e < 4; ++e) { v0[e] *= sigm_f(bf2f((u16)g[qq][e])); v1[e] *= sigm_f(bf2f((u16)g[qq][4 + e])); }
;             if (ex) {
;               float* mp = (float*)(ws + OFF_MFC) + ((size_t)sb * 1024 + (R_ - ROWS_LAT)) * 1024 + cc_;
;               *reinterpret_cast<f32x4*>(mp) = v0; *reinterpret_cast<f32x4*>(mp + 4) = v1;
.LBB0_241:
	s_andn2_b64 vcc, exec, s[4:5]
	s_cbranch_vccnz .LBB0_339
	s_add_u32 s8, s96, 0xfe00000
	s_addc_u32 s9, s97, 0
	s_add_u32 s3, s96, 0x14200000
	s_addc_u32 s14, s97, 0
	s_cmp_lg_u32 s23, 0
	s_cselect_b64 s[16:17], -1, 0
	s_cmp_gt_i32 s0, 0
	s_cselect_b64 s[12:13], -1, 0
	s_lshl_b32 s4, s0, 10
	s_ashr_i32 s5, s4, 31
	s_lshl_b64 s[4:5], s[4:5], 1
	s_add_u32 s1, s96, s4
	s_addc_u32 s4, s97, s5
	s_add_u32 s10, s1, 0x2b800000
	s_addc_u32 s11, s4, 0
	s_ashr_i32 s1, s0, 31
	s_lshl_b64 s[4:5], s[0:1], 22
	s_add_u32 s4, s96, s4
	v_lshlrev_b32_e32 v16, 5, v226
	v_lshlrev_b32_e32 v17, 3, v227
	s_addc_u32 s5, s97, s5
	v_ashrrev_i32_e32 v175, 31, v174
	v_or3_b32 v168, v16, v17, s22
	v_or_b32_e32 v178, 16, v174
	s_cmp_lt_i32 s0, 2
	v_ashrrev_i32_e32 v169, 31, v168
	v_lshlrev_b64 v[180:181], 11, v[174:175]
	v_ashrrev_i32_e32 v179, 31, v178
	s_cselect_b32 s0, s8, s3
	v_mov_b64_e32 v[16:17], s[10:11]
	s_movk_i32 s3, 0x1800
	v_lshlrev_b64 v[172:173], 1, v[168:169]
	v_lshl_add_u64 v[128:129], s[8:9], 0, v[180:181]
	v_lshlrev_b64 v[176:177], 11, v[178:179]
	s_cselect_b32 s1, s9, s14
	v_mad_i64_i32 v[18:19], s[14:15], v174, s3, v[16:17]
	v_lshl_add_u64 v[170:171], v[128:129], 0, v[172:173]
	v_mad_i64_i32 v[16:17], s[14:15], v178, s3, v[16:17]
	v_lshl_add_u64 v[128:129], s[8:9], 0, v[176:177]
	v_lshl_add_u64 v[18:19], v[18:19], 0, v[172:173]
	v_lshl_add_u64 v[16:17], v[16:17], 0, v[172:173]
	v_lshl_add_u64 v[128:129], v[128:129], 0, v[172:173]
	global_load_dwordx4 v[148:151], v[18:19], off offset:256 nt
	global_load_dwordx4 v[144:147], v[170:171], off offset:256
	global_load_dwordx4 v[140:143], v[16:17], off nt
	global_load_dwordx4 v[136:139], v[128:129], off
	global_load_dwordx4 v[132:135], v[16:17], off offset:256 nt
	s_nop 0
	global_load_dwordx4 v[128:131], v[128:129], off offset:256
	s_nop 0
	global_load_dwordx4 v[154:157], v[18:19], off nt
	global_load_dwordx4 v[232:235], v[170:171], off
	s_mov_b64 s[14:15], 0x30000
	v_lshl_add_u64 v[248:249], v[18:19], 0, s[14:15]
	v_lshl_add_u64 v[250:251], v[16:17], 0, s[14:15]
	global_load_dwordx4 v[244:247], v[248:249], off
	global_load_dwordx4 v[244:247], v[248:249], off offset:256
	global_load_dwordx4 v[244:247], v[250:251], off
	global_load_dwordx4 v[244:247], v[250:251], off offset:256
	s_mov_b64 s[14:15], 0xc0000
	v_lshl_add_u64 v[248:249], v[18:19], 0, s[14:15]
	v_lshl_add_u64 v[250:251], v[16:17], 0, s[14:15]
	global_load_dwordx4 v[244:247], v[248:249], off
	global_load_dwordx4 v[244:247], v[248:249], off offset:256
	global_load_dwordx4 v[244:247], v[250:251], off
	global_load_dwordx4 v[244:247], v[250:251], off offset:256
	s_mov_b64 s[14:15], 0xf0000
	v_lshl_add_u64 v[248:249], v[18:19], 0, s[14:15]
	v_lshl_add_u64 v[250:251], v[16:17], 0, s[14:15]
	global_load_dwordx4 v[244:247], v[248:249], off
	global_load_dwordx4 v[244:247], v[248:249], off offset:256
	global_load_dwordx4 v[244:247], v[250:251], off
	global_load_dwordx4 v[244:247], v[250:251], off offset:256
	s_cmp_eq_u32 s23, 0
	s_waitcnt vmcnt(12)
	v_lshlrev_b32_e32 v17, 16, v156
	v_mul_f32_e32 v17, 0xbfb8aa3b, v17
	v_lshlrev_b32_e32 v16, 16, v154
	v_exp_f32_e32 v18, v17
	v_and_b32_e32 v17, 0xffff0000, v154
	v_mul_f32_e32 v16, 0xbfb8aa3b, v16
	v_mul_f32_e32 v17, 0xbfb8aa3b, v17
	v_exp_f32_e32 v16, v16
	v_exp_f32_e32 v17, v17
	s_nop 0
	v_pk_add_f32 v[16:17], v[16:17], 1.0 op_sel_hi:[1,0]
	s_nop 0
	s_nop 0
	v_rcp_f32_e32 v17, v17
	s_nop 0
	s_nop 0
	v_rcp_f32_e32 v16, v16
	s_nop 0
	v_pk_mul_f32 v[152:153], v[120:121], v[16:17]
	v_and_b32_e32 v16, 0xffff0000, v156
	v_mul_f32_e32 v16, 0xbfb8aa3b, v16
	v_exp_f32_e32 v19, v16
	s_nop 0
	v_pk_add_f32 v[16:17], v[18:19], 1.0 op_sel_hi:[1,0]
	s_nop 0
	s_nop 0
	v_rcp_f32_e32 v17, v17
	s_nop 0
	s_nop 0
	v_rcp_f32_e32 v16, v16
	s_nop 0
	v_pk_mul_f32 v[158:159], v[112:113], v[16:17]
	v_lshlrev_b32_e32 v17, 16, v157
	v_mul_f32_e32 v17, 0xbfb8aa3b, v17
	v_lshlrev_b32_e32 v16, 16, v155
	v_exp_f32_e32 v18, v17
	v_and_b32_e32 v17, 0xffff0000, v155
	v_mul_f32_e32 v16, 0xbfb8aa3b, v16
	v_mul_f32_e32 v17, 0xbfb8aa3b, v17
	v_exp_f32_e32 v16, v16
	v_exp_f32_e32 v17, v17
	s_nop 0
	v_pk_add_f32 v[16:17], v[16:17], 1.0 op_sel_hi:[1,0]
	s_nop 0
	s_nop 0
	v_rcp_f32_e32 v17, v17
	s_nop 0
	s_nop 0
	v_rcp_f32_e32 v16, v16
	s_nop 0
	v_pk_mul_f32 v[154:155], v[122:123], v[16:17]
	v_and_b32_e32 v16, 0xffff0000, v157
	v_mul_f32_e32 v16, 0xbfb8aa3b, v16
	v_exp_f32_e32 v19, v16
	s_nop 0
	v_pk_add_f32 v[16:17], v[18:19], 1.0 op_sel_hi:[1,0]
	s_nop 0
	s_nop 0
	v_rcp_f32_e32 v17, v17
	s_nop 0
	s_nop 0
	v_rcp_f32_e32 v16, v16
	s_nop 0
	v_pk_mul_f32 v[160:161], v[114:115], v[16:17]
	v_lshlrev_b64 v[16:17], 12, v[174:175]
	v_lshl_add_u64 v[182:183], s[4:5], 0, v[16:17]
	s_cbranch_scc1 .LBB0_244
	v_lshl_add_u64 v[16:17], v[168:169], 2, v[182:183]
	v_lshl_add_u64 v[18:19], v[16:17], 0, s[52:53]
	v_add_co_u32_e32 v16, vcc, 0x36649000, v16
	s_nop 1
	v_addc_co_u32_e32 v17, vcc, 0, v17, vcc
	global_store_dwordx4 v[16:17], v[152:155], off offset:1792
	global_store_dwordx4 v[18:19], v[158:161], off offset:16
	v_cndmask_b32_e64 v16, 0, 1, s[12:13]
	v_cmp_ne_u32_e64 s[12:13], 1, v16
	s_cbranch_execz .LBB0_245
	s_branch .LBB0_248

; DEV float bf2f(u16 h) { return __uint_as_float(((unsigned)h) << 16); }
; DEV void phase_gemm(const Params& p, int l, int mode) {
;     ...
;               if (rd) {
; #pragma unroll
;                 for (int e = 0; e < 4; ++e) { v0[e] += bf2f((u16)pm_[qq][e]); v1[e] += bf2f((u16)pm_[qq][4 + e]); }
;               }
.LBB0_245:
	s_and_b64 vcc, exec, s[12:13]
	s_cbranch_vccnz .LBB0_247
	v_and_b32_e32 v157, 0xffff0000, v232
	v_lshlrev_b32_e32 v156, 16, v232
	v_pk_add_f32 v[152:153], v[152:153], v[156:157]
	v_and_b32_e32 v157, 0xffff0000, v234
	v_lshlrev_b32_e32 v156, 16, v234
	v_pk_add_f32 v[158:159], v[158:159], v[156:157]
	v_and_b32_e32 v157, 0xffff0000, v233
	v_lshlrev_b32_e32 v156, 16, v233
	v_and_b32_e32 v17, 0xffff0000, v235
	v_lshlrev_b32_e32 v16, 16, v235
	v_pk_add_f32 v[154:155], v[154:155], v[156:157]
	v_pk_add_f32 v[160:161], v[160:161], v[16:17]

; DEV float bf2f(u16 h) { return __uint_as_float(((unsigned)h) << 16); }
; DEV float sigm_f(float v) { return 1.f / (1.f + __expf(-v)); }
; DEV void phase_gemm(const Params& p, int l, int mode) {
;     ...
;           for (int qq = 0; qq < 4; ++qq) { M1_ADDR(hb * 4 + qq); g[qq] = __builtin_nontemporal_load(reinterpret_cast<const bf16x8*>(MG + R_ * 3072 + sb * 1024 + cc_)); pm_[qq] = *reinterpret_cast<const bf16x8*>(MH + R_ * 1024 + cc_); }
; #pragma unroll
;           for (int qq = 0; qq < 4; ++qq) {
;             M1_ADDR(hb * 4 + qq);
;             f32x4 v0 = acc[ai_][bj_][m_][0], v1 = acc[ai_][bj_][m_][1];
; #pragma unroll
;             for (int e = 0; e < 4; ++e) { v0[e] *= sigm_f(bf2f((u16)g[qq][e])); v1[e] *= sigm_f(bf2f((u16)g[qq][4 + e])); }
;             if (ex) {
;               float* mp = (float*)(ws + OFF_MFC) + ((size_t)sb * 1024 + (R_ - ROWS_LAT)) * 1024 + cc_;
;               *reinterpret_cast<f32x4*>(mp) = v0; *reinterpret_cast<f32x4*>(mp + 4) = v1;
;             } else {
;               if (rd) {
; #pragma unroll
;                 for (int e = 0; e < 4; ++e) { v0[e] += bf2f((u16)pm_[qq][e]); v1[e] += bf2f((u16)pm_[qq][4 + e]); }
;               }
.LBB0_266:
	v_or_b32_e32 v184, 32, v174
	v_ashrrev_i32_e32 v185, 31, v184
	v_or_b32_e32 v178, 48, v174
	v_lshlrev_b64 v[180:181], 11, v[184:185]
	v_ashrrev_i32_e32 v179, 31, v178
	v_mov_b64_e32 v[16:17], s[10:11]
	v_lshl_add_u64 v[128:129], s[8:9], 0, v[180:181]
	v_lshlrev_b64 v[176:177], 11, v[178:179]
	v_mad_i64_i32 v[18:19], s[16:17], v184, s3, v[16:17]
	v_lshl_add_u64 v[182:183], v[128:129], 0, v[172:173]
	v_mad_i64_i32 v[16:17], s[16:17], v178, s3, v[16:17]
	v_lshl_add_u64 v[128:129], s[8:9], 0, v[176:177]
	v_lshl_add_u64 v[18:19], v[18:19], 0, v[172:173]
	v_lshl_add_u64 v[16:17], v[16:17], 0, v[172:173]
	v_lshl_add_u64 v[128:129], v[128:129], 0, v[172:173]
	global_load_dwordx4 v[148:151], v[18:19], off offset:256 nt
	global_load_dwordx4 v[144:147], v[182:183], off offset:256
	global_load_dwordx4 v[140:143], v[16:17], off nt
	global_load_dwordx4 v[136:139], v[128:129], off
	global_load_dwordx4 v[132:135], v[16:17], off offset:256 nt
	s_nop 0
	global_load_dwordx4 v[128:131], v[128:129], off offset:256
	s_nop 0
	global_load_dwordx4 v[154:157], v[18:19], off nt
	global_load_dwordx4 v[232:235], v[182:183], off
	s_waitcnt vmcnt(0)
	v_lshlrev_b32_e32 v17, 16, v156
	v_mul_f32_e32 v17, 0xbfb8aa3b, v17
	v_lshlrev_b32_e32 v16, 16, v154
	v_exp_f32_e32 v18, v17
	v_and_b32_e32 v17, 0xffff0000, v154
	v_mul_f32_e32 v16, 0xbfb8aa3b, v16
	v_mul_f32_e32 v17, 0xbfb8aa3b, v17
	v_exp_f32_e32 v16, v16
	v_exp_f32_e32 v17, v17
	s_nop 0
	v_pk_add_f32 v[16:17], v[16:17], 1.0 op_sel_hi:[1,0]
	s_nop 0
	s_nop 0
	v_rcp_f32_e32 v17, v17
	s_nop 0
	s_nop 0
	v_rcp_f32_e32 v16, v16
	s_nop 0
	v_pk_mul_f32 v[152:153], v[56:57], v[16:17]
	v_and_b32_e32 v16, 0xffff0000, v156
	v_mul_f32_e32 v16, 0xbfb8aa3b, v16
	v_exp_f32_e32 v19, v16
	s_nop 0
	v_pk_add_f32 v[16:17], v[18:19], 1.0 op_sel_hi:[1,0]
	s_nop 0
	s_nop 0
	v_rcp_f32_e32 v17, v17
	s_nop 0
	s_nop 0
	v_rcp_f32_e32 v16, v16
	s_nop 0
	v_pk_mul_f32 v[158:159], v[48:49], v[16:17]
	v_lshlrev_b32_e32 v17, 16, v157
	v_mul_f32_e32 v17, 0xbfb8aa3b, v17
	v_lshlrev_b32_e32 v16, 16, v155
	v_exp_f32_e32 v156, v17
	v_and_b32_e32 v17, 0xffff0000, v155
	v_mul_f32_e32 v16, 0xbfb8aa3b, v16
	v_mul_f32_e32 v17, 0xbfb8aa3b, v17
	v_exp_f32_e32 v16, v16
	v_exp_f32_e32 v17, v17
	s_nop 0
	v_pk_add_f32 v[154:155], v[16:17], 1.0 op_sel_hi:[1,0]
	s_nop 0
	s_nop 0
	v_rcp_f32_e32 v17, v155
	s_nop 0
	s_nop 0
	v_rcp_f32_e32 v16, v154
	s_nop 0
	v_pk_mul_f32 v[154:155], v[58:59], v[16:17]
	v_and_b32_e32 v16, 0xffff0000, v157
	v_mul_f32_e32 v16, 0xbfb8aa3b, v16
	v_exp_f32_e32 v157, v16
	s_nop 0
	v_pk_add_f32 v[16:17], v[156:157], 1.0 op_sel_hi:[1,0]
	s_nop 0
	s_nop 0
	v_rcp_f32_e32 v17, v17
	s_nop 0
	s_nop 0
	v_rcp_f32_e32 v16, v16
	s_nop 0
	v_pk_mul_f32 v[160:161], v[50:51], v[16:17]
	v_lshlrev_b64 v[16:17], 12, v[184:185]
	s_and_b64 vcc, exec, s[14:15]
	v_lshl_add_u64 v[184:185], s[4:5], 0, v[16:17]
	s_cbranch_vccnz .LBB0_268
	v_lshl_add_u64 v[16:17], v[168:169], 2, v[184:185]
	v_lshl_add_u64 v[18:19], v[16:17], 0, s[52:53]
	v_add_co_u32_e32 v16, vcc, 0x36649000, v16
	s_nop 1
	v_addc_co_u32_e32 v17, vcc, 0, v17, vcc
	global_store_dwordx4 v[16:17], v[152:155], off offset:1792
	global_store_dwordx4 v[18:19], v[158:161], off offset:16
	s_cbranch_execz .LBB0_269
	s_branch .LBB0_272
.LBB0_268:
.LBB0_269:
	s_and_b64 vcc, exec, s[12:13]
	s_cbranch_vccnz .LBB0_271
	v_and_b32_e32 v157, 0xffff0000, v232
	v_lshlrev_b32_e32 v156, 16, v232
	v_pk_add_f32 v[152:153], v[152:153], v[156:157]
	v_and_b32_e32 v157, 0xffff0000, v234
	v_lshlrev_b32_e32 v156, 16, v234
	v_pk_add_f32 v[158:159], v[158:159], v[156:157]
	v_and_b32_e32 v157, 0xffff0000, v233
	v_lshlrev_b32_e32 v156, 16, v233
	v_and_b32_e32 v17, 0xffff0000, v235
	v_lshlrev_b32_e32 v16, 16, v235
	v_pk_add_f32 v[154:155], v[154:155], v[156:157]
	v_pk_add_f32 v[160:161], v[160:161], v[16:17]

; DEV float bf2f(u16 h) { return __uint_as_float(((unsigned)h) << 16); }
; DEV float sigm_f(float v) { return 1.f / (1.f + __expf(-v)); }
; DEV void phase_gemm(const Params& p, int l, int mode) {
;     ...
;           for (int qq = 0; qq < 4; ++qq) { M1_ADDR(hb * 4 + qq); g[qq] = __builtin_nontemporal_load(reinterpret_cast<const bf16x8*>(MG + R_ * 3072 + sb * 1024 + cc_)); pm_[qq] = *reinterpret_cast<const bf16x8*>(MH + R_ * 1024 + cc_); }
; #pragma unroll
;           for (int qq = 0; qq < 4; ++qq) {
;             M1_ADDR(hb * 4 + qq);
;             f32x4 v0 = acc[ai_][bj_][m_][0], v1 = acc[ai_][bj_][m_][1];
; #pragma unroll
;             for (int e = 0; e < 4; ++e) { v0[e] *= sigm_f(bf2f((u16)g[qq][e])); v1[e] *= sigm_f(bf2f((u16)g[qq][4 + e])); }
;             if (ex) {
;               float* mp = (float*)(ws + OFF_MFC) + ((size_t)sb * 1024 + (R_ - ROWS_LAT)) * 1024 + cc_;
;               *reinterpret_cast<f32x4*>(mp) = v0; *reinterpret_cast<f32x4*>(mp + 4) = v1;
.LBB0_290:
	v_add_u32_e32 v176, 0x80, v174
	v_ashrrev_i32_e32 v177, 31, v176
	v_add_u32_e32 v178, 0x90, v174
	v_lshlrev_b64 v[180:181], 11, v[176:177]
	v_ashrrev_i32_e32 v179, 31, v178
	v_mov_b64_e32 v[16:17], s[10:11]
	v_lshl_add_u64 v[128:129], s[8:9], 0, v[180:181]
	v_lshlrev_b64 v[174:175], 11, v[178:179]
	v_mad_i64_i32 v[18:19], s[16:17], v176, s3, v[16:17]
	v_lshl_add_u64 v[182:183], v[128:129], 0, v[172:173]
	v_mad_i64_i32 v[16:17], s[16:17], v178, s3, v[16:17]
	v_lshl_add_u64 v[128:129], s[8:9], 0, v[174:175]
	v_lshl_add_u64 v[18:19], v[18:19], 0, v[172:173]
	v_lshl_add_u64 v[16:17], v[16:17], 0, v[172:173]
	v_lshl_add_u64 v[128:129], v[128:129], 0, v[172:173]
	global_load_dwordx4 v[148:151], v[18:19], off offset:256 nt
	global_load_dwordx4 v[144:147], v[182:183], off offset:256
	global_load_dwordx4 v[140:143], v[16:17], off nt
	global_load_dwordx4 v[136:139], v[128:129], off
	global_load_dwordx4 v[132:135], v[16:17], off offset:256 nt
	s_nop 0
	global_load_dwordx4 v[128:131], v[128:129], off offset:256
	s_nop 0
	global_load_dwordx4 v[154:157], v[18:19], off nt
	global_load_dwordx4 v[232:235], v[182:183], off
	s_waitcnt vmcnt(0)
	v_lshlrev_b32_e32 v17, 16, v156
	v_mul_f32_e32 v17, 0xbfb8aa3b, v17
	v_lshlrev_b32_e32 v16, 16, v154
	v_exp_f32_e32 v18, v17
	v_and_b32_e32 v17, 0xffff0000, v154
	v_mul_f32_e32 v16, 0xbfb8aa3b, v16
	v_mul_f32_e32 v17, 0xbfb8aa3b, v17
	v_exp_f32_e32 v16, v16
	v_exp_f32_e32 v17, v17
	s_nop 0
	v_pk_add_f32 v[16:17], v[16:17], 1.0 op_sel_hi:[1,0]
	s_nop 0
	s_nop 0
	v_rcp_f32_e32 v17, v17
	s_nop 0
	s_nop 0
	v_rcp_f32_e32 v16, v16
	s_nop 0
	v_pk_mul_f32 v[152:153], v[124:125], v[16:17]
	v_and_b32_e32 v16, 0xffff0000, v156
	v_mul_f32_e32 v16, 0xbfb8aa3b, v16
	v_exp_f32_e32 v19, v16
	s_nop 0
	v_pk_add_f32 v[16:17], v[18:19], 1.0 op_sel_hi:[1,0]
	s_nop 0
	s_nop 0
	v_rcp_f32_e32 v17, v17
	s_nop 0
	s_nop 0
	v_rcp_f32_e32 v16, v16
	s_nop 0
	v_pk_mul_f32 v[158:159], v[116:117], v[16:17]
	v_lshlrev_b32_e32 v17, 16, v157
	v_mul_f32_e32 v17, 0xbfb8aa3b, v17
	v_lshlrev_b32_e32 v16, 16, v155
	v_exp_f32_e32 v156, v17
	v_and_b32_e32 v17, 0xffff0000, v155
	v_mul_f32_e32 v16, 0xbfb8aa3b, v16
	v_mul_f32_e32 v17, 0xbfb8aa3b, v17
	v_exp_f32_e32 v16, v16
	v_exp_f32_e32 v17, v17
	s_nop 0
	v_pk_add_f32 v[154:155], v[16:17], 1.0 op_sel_hi:[1,0]
	s_nop 0
	s_nop 0
	v_rcp_f32_e32 v17, v155
	s_nop 0
	s_nop 0
	v_rcp_f32_e32 v16, v154
	s_nop 0
	v_pk_mul_f32 v[154:155], v[126:127], v[16:17]
	v_and_b32_e32 v16, 0xffff0000, v157
	v_mul_f32_e32 v16, 0xbfb8aa3b, v16
	v_exp_f32_e32 v157, v16
	s_nop 0
	v_pk_add_f32 v[16:17], v[156:157], 1.0 op_sel_hi:[1,0]
	s_nop 0
	s_nop 0
	v_rcp_f32_e32 v17, v17
	s_nop 0
	s_nop 0
	v_rcp_f32_e32 v16, v16
	s_nop 0
	v_pk_mul_f32 v[160:161], v[118:119], v[16:17]
	v_lshlrev_b64 v[16:17], 12, v[176:177]
	s_and_b64 vcc, exec, s[14:15]
	v_lshl_add_u64 v[184:185], s[4:5], 0, v[16:17]
	s_cbranch_vccnz .LBB0_292
	v_lshl_add_u64 v[16:17], v[168:169], 2, v[184:185]
	v_lshl_add_u64 v[18:19], v[16:17], 0, s[52:53]
	v_add_co_u32_e32 v16, vcc, 0x36649000, v16
	s_nop 1
	v_addc_co_u32_e32 v17, vcc, 0, v17, vcc
	global_store_dwordx4 v[16:17], v[152:155], off offset:1792
	global_store_dwordx4 v[18:19], v[158:161], off offset:16
	s_cbranch_execz .LBB0_293
	s_branch .LBB0_296

; DEV float bf2f(u16 h) { return __uint_as_float(((unsigned)h) << 16); }
; DEV float sigm_f(float v) { return 1.f / (1.f + __expf(-v)); }
; DEV void phase_gemm(const Params& p, int l, int mode) {
;     ...
;           for (int qq = 0; qq < 4; ++qq) { M1_ADDR(hb * 4 + qq); g[qq] = __builtin_nontemporal_load(reinterpret_cast<const bf16x8*>(MG + R_ * 3072 + sb * 1024 + cc_)); pm_[qq] = *reinterpret_cast<const bf16x8*>(MH + R_ * 1024 + cc_); }
; #pragma unroll
;           for (int qq = 0; qq < 4; ++qq) {
;             M1_ADDR(hb * 4 + qq);
;             f32x4 v0 = acc[ai_][bj_][m_][0], v1 = acc[ai_][bj_][m_][1];
; #pragma unroll
;             for (int e = 0; e < 4; ++e) { v0[e] *= sigm_f(bf2f((u16)g[qq][e])); v1[e] *= sigm_f(bf2f((u16)g[qq][4 + e])); }
;             if (ex) {
;               float* mp = (float*)(ws + OFF_MFC) + ((size_t)sb * 1024 + (R_ - ROWS_LAT)) * 1024 + cc_;
;               *reinterpret_cast<f32x4*>(mp) = v0; *reinterpret_cast<f32x4*>(mp + 4) = v1;
.LBB0_314:
	v_or_b32_e32 v182, 32, v176
	v_ashrrev_i32_e32 v183, 31, v182
	v_or_b32_e32 v176, 48, v176
	v_lshlrev_b64 v[178:179], 11, v[182:183]
	v_ashrrev_i32_e32 v177, 31, v176
	v_mov_b64_e32 v[16:17], s[10:11]
	v_lshl_add_u64 v[128:129], s[8:9], 0, v[178:179]
	v_lshlrev_b64 v[174:175], 11, v[176:177]
	v_mad_i64_i32 v[18:19], s[10:11], v182, s3, v[16:17]
	v_lshl_add_u64 v[180:181], v[128:129], 0, v[172:173]
	v_mad_i64_i32 v[16:17], s[10:11], v176, s3, v[16:17]
	v_lshl_add_u64 v[128:129], s[8:9], 0, v[174:175]
	v_lshl_add_u64 v[18:19], v[18:19], 0, v[172:173]
	v_lshl_add_u64 v[16:17], v[16:17], 0, v[172:173]
	v_lshl_add_u64 v[128:129], v[128:129], 0, v[172:173]
	global_load_dwordx4 v[148:151], v[18:19], off offset:256 nt
	global_load_dwordx4 v[144:147], v[180:181], off offset:256
	global_load_dwordx4 v[140:143], v[16:17], off nt
	global_load_dwordx4 v[136:139], v[128:129], off
	global_load_dwordx4 v[132:135], v[16:17], off offset:256 nt
	s_nop 0
	global_load_dwordx4 v[128:131], v[128:129], off offset:256
	s_nop 0
	global_load_dwordx4 v[154:157], v[18:19], off nt
	global_load_dwordx4 v[232:235], v[180:181], off
	s_waitcnt vmcnt(0)
	v_lshlrev_b32_e32 v17, 16, v156
	v_mul_f32_e32 v17, 0xbfb8aa3b, v17
	v_lshlrev_b32_e32 v16, 16, v154
	v_exp_f32_e32 v18, v17
	v_and_b32_e32 v17, 0xffff0000, v154
	v_mul_f32_e32 v16, 0xbfb8aa3b, v16
	v_mul_f32_e32 v17, 0xbfb8aa3b, v17
	v_exp_f32_e32 v16, v16
	v_exp_f32_e32 v17, v17
	s_nop 0
	v_pk_add_f32 v[16:17], v[16:17], 1.0 op_sel_hi:[1,0]
	s_nop 0
	s_nop 0
	v_rcp_f32_e32 v17, v17
	s_nop 0
	s_nop 0
	v_rcp_f32_e32 v16, v16
	s_nop 0
	v_pk_mul_f32 v[152:153], v[60:61], v[16:17]
	v_and_b32_e32 v16, 0xffff0000, v156
	v_mul_f32_e32 v16, 0xbfb8aa3b, v16
	v_exp_f32_e32 v19, v16
	s_nop 0
	v_pk_add_f32 v[16:17], v[18:19], 1.0 op_sel_hi:[1,0]
	s_nop 0
	s_nop 0
	v_rcp_f32_e32 v17, v17
	s_nop 0
	s_nop 0
	v_rcp_f32_e32 v16, v16
	s_nop 0
	v_pk_mul_f32 v[158:159], v[52:53], v[16:17]
	v_lshlrev_b32_e32 v17, 16, v157
	v_mul_f32_e32 v17, 0xbfb8aa3b, v17
	v_lshlrev_b32_e32 v16, 16, v155
	v_exp_f32_e32 v156, v17
	v_and_b32_e32 v17, 0xffff0000, v155
	v_mul_f32_e32 v16, 0xbfb8aa3b, v16
	v_mul_f32_e32 v17, 0xbfb8aa3b, v17
	v_exp_f32_e32 v16, v16
	v_exp_f32_e32 v17, v17
	s_nop 0
	v_pk_add_f32 v[154:155], v[16:17], 1.0 op_sel_hi:[1,0]
	s_nop 0
	s_nop 0
	v_rcp_f32_e32 v17, v155
	s_nop 0
	s_nop 0
	v_rcp_f32_e32 v16, v154
	s_nop 0
	v_pk_mul_f32 v[154:155], v[62:63], v[16:17]
	v_and_b32_e32 v16, 0xffff0000, v157
	v_mul_f32_e32 v16, 0xbfb8aa3b, v16
	v_exp_f32_e32 v157, v16
	s_nop 0
	v_pk_add_f32 v[16:17], v[156:157], 1.0 op_sel_hi:[1,0]
	s_nop 0
	s_nop 0
	v_rcp_f32_e32 v17, v17
	s_nop 0
	s_nop 0
	v_rcp_f32_e32 v16, v16
	s_nop 0
	v_pk_mul_f32 v[160:161], v[54:55], v[16:17]
	v_lshlrev_b64 v[16:17], 12, v[182:183]
	s_and_b64 vcc, exec, s[14:15]
	v_lshl_add_u64 v[172:173], s[4:5], 0, v[16:17]
	s_cbranch_vccnz .LBB0_316
	v_lshl_add_u64 v[16:17], v[168:169], 2, v[172:173]
	v_lshl_add_u64 v[18:19], v[16:17], 0, s[52:53]
	v_add_co_u32_e32 v16, vcc, 0x36649000, v16
	s_nop 1
	v_addc_co_u32_e32 v17, vcc, 0, v17, vcc
	global_store_dwordx4 v[16:17], v[152:155], off offset:1792
	global_store_dwordx4 v[18:19], v[158:161], off offset:16
	s_cbranch_execz .LBB0_317
	s_branch .LBB0_320
